# attention first half-step: waves 4-7 do the O rescale + partialSM tail before the barrier, waves 0-3 after it (the two waves of a SIMD swap the lead each half-step)
# baseline (speedup 1.0000x reference)
.Lp1join_fox_1:
	v_cmp_gt_f32_e32 vcc, 1.0, v108
	s_cmp_lt_u32 s5, 4
	s_cbranch_scc1 .Lxbar_fox
	s_cbranch_vccz .Lxb_fox
	s_and_saveexec_b64 s[0:1], s[38:39]
	ds_write_b32 v185, v108 offset:128
	s_or_b64 exec, exec, s[0:1]
	s_waitcnt lgkmcnt(0)
	ds_read_b128 v[88:91], v184 offset:224
	ds_read_b128 v[92:95], v184 offset:192
	ds_read_b128 v[110:113], v184 offset:160
	ds_read_b128 v[202:205], v184 offset:128
	s_waitcnt lgkmcnt(3)
	v_mul_f32 v64, v64, v90
	v_mul_f32 v65, v65, v91
	s_waitcnt lgkmcnt(2)
	v_mul_f32 v60, v60, v94
	v_mul_f32 v61, v61, v95
	s_waitcnt lgkmcnt(1)
	v_mul_f32 v56, v56, v112
	v_mul_f32 v57, v57, v113
	s_waitcnt lgkmcnt(0)
	v_mul_f32 v52, v52, v204
	v_mul_f32 v53, v53, v205
	v_mul_f32 v62, v62, v88
	v_mul_f32 v63, v63, v89
	v_mul_f32 v58, v58, v92
	v_mul_f32 v59, v59, v93
	v_mul_f32 v54, v54, v110
	v_mul_f32 v55, v55, v111
	v_mul_f32 v50, v50, v202
	v_mul_f32 v51, v51, v203
	v_mul_f32 v48, v48, v90
	v_mul_f32 v49, v49, v91
	v_mul_f32 v44, v44, v94
	v_mul_f32 v45, v45, v95
	v_mul_f32 v40, v40, v112
	v_mul_f32 v41, v41, v113
	v_mul_f32 v36, v36, v204
	v_mul_f32 v37, v37, v205
	v_mul_f32 v46, v46, v88
	v_mul_f32 v47, v47, v89
	v_mul_f32 v42, v42, v92
	v_mul_f32 v43, v43, v93
	v_mul_f32 v38, v38, v110
	v_mul_f32 v39, v39, v111
	v_mul_f32 v34, v34, v202
	v_mul_f32 v35, v35, v203
	v_mul_f32 v32, v32, v90
	v_mul_f32 v33, v33, v91
	v_mul_f32 v28, v28, v94
	v_mul_f32 v29, v29, v95
	v_mul_f32 v24, v24, v112
	v_mul_f32 v25, v25, v113
	v_mul_f32 v20, v20, v204
	v_mul_f32 v21, v21, v205
	v_mul_f32 v30, v30, v88
	v_mul_f32 v31, v31, v89
	v_mul_f32 v26, v26, v92
	v_mul_f32 v27, v27, v93
	v_mul_f32 v22, v22, v110
	v_mul_f32 v23, v23, v111
	v_mul_f32 v18, v18, v202
	v_mul_f32 v19, v19, v203
	v_mul_f32 v16, v16, v90
	v_mul_f32 v17, v17, v91
	v_mul_f32 v12, v12, v94
	v_mul_f32 v13, v13, v95
	v_mul_f32 v8, v8, v112
	v_mul_f32 v9, v9, v113
	v_mul_f32 v4, v4, v204
	v_mul_f32 v5, v5, v205
	v_mul_f32 v14, v14, v88
	v_mul_f32 v15, v15, v89
	v_mul_f32 v10, v10, v92
	v_mul_f32 v11, v11, v93
	v_mul_f32 v6, v6, v110
	v_mul_f32 v7, v7, v111
	v_mul_f32 v2, v2, v202
	v_mul_f32 v3, v3, v203

.Lxbar_fox:
	s_waitcnt vmcnt(1)
	ds_write_b128 v193, v[154:157] offset:32768
	s_waitcnt vmcnt(0)
	ds_write_b128 v193, v[158:161] offset:40960
	s_waitcnt lgkmcnt(0)
	s_barrier
	ds_write_b128 v194, v[146:149]
	ds_write_b128 v195, v[150:153]
	s_cmp_lt_u32 s5, 4
	s_cbranch_scc0 .Lxjoin_fox
	v_cmp_gt_f32_e32 vcc, 1.0, v108
	s_cbranch_vccz .LBB0_651
	s_and_saveexec_b64 s[0:1], s[38:39]
	ds_write_b32 v185, v108 offset:128
	s_or_b64 exec, exec, s[0:1]
	s_waitcnt lgkmcnt(0)
	ds_read_b128 v[88:91], v184 offset:224
	ds_read_b128 v[92:95], v184 offset:192
	ds_read_b128 v[110:113], v184 offset:160
	ds_read_b128 v[202:205], v184 offset:128
	s_waitcnt lgkmcnt(3)
	v_mul_f32 v64, v64, v90
	v_mul_f32 v65, v65, v91
	s_waitcnt lgkmcnt(2)
	v_mul_f32 v60, v60, v94
	v_mul_f32 v61, v61, v95
	s_waitcnt lgkmcnt(1)
	v_mul_f32 v56, v56, v112
	v_mul_f32 v57, v57, v113
	s_waitcnt lgkmcnt(0)
	v_mul_f32 v52, v52, v204
	v_mul_f32 v53, v53, v205
	v_mul_f32 v62, v62, v88
	v_mul_f32 v63, v63, v89
	v_mul_f32 v58, v58, v92
	v_mul_f32 v59, v59, v93
	v_mul_f32 v54, v54, v110
	v_mul_f32 v55, v55, v111
	v_mul_f32 v50, v50, v202
	v_mul_f32 v51, v51, v203
	v_mul_f32 v48, v48, v90
	v_mul_f32 v49, v49, v91
	v_mul_f32 v44, v44, v94
	v_mul_f32 v45, v45, v95
	v_mul_f32 v40, v40, v112
	v_mul_f32 v41, v41, v113
	v_mul_f32 v36, v36, v204
	v_mul_f32 v37, v37, v205
	v_mul_f32 v46, v46, v88
	v_mul_f32 v47, v47, v89
	v_mul_f32 v42, v42, v92
	v_mul_f32 v43, v43, v93
	v_mul_f32 v38, v38, v110
	v_mul_f32 v39, v39, v111
	v_mul_f32 v34, v34, v202
	v_mul_f32 v35, v35, v203
	v_mul_f32 v32, v32, v90
	v_mul_f32 v33, v33, v91
	v_mul_f32 v28, v28, v94
	v_mul_f32 v29, v29, v95
	v_mul_f32 v24, v24, v112
	v_mul_f32 v25, v25, v113
	v_mul_f32 v20, v20, v204
	v_mul_f32 v21, v21, v205
	v_mul_f32 v30, v30, v88
	v_mul_f32 v31, v31, v89
	v_mul_f32 v26, v26, v92
	v_mul_f32 v27, v27, v93
	v_mul_f32 v22, v22, v110
	v_mul_f32 v23, v23, v111
	v_mul_f32 v18, v18, v202
	v_mul_f32 v19, v19, v203
	v_mul_f32 v16, v16, v90
	v_mul_f32 v17, v17, v91
	v_mul_f32 v12, v12, v94
	v_mul_f32 v13, v13, v95
	v_mul_f32 v8, v8, v112
	v_mul_f32 v9, v9, v113
	v_mul_f32 v4, v4, v204
	v_mul_f32 v5, v5, v205
	v_mul_f32 v14, v14, v88
	v_mul_f32 v15, v15, v89
	v_mul_f32 v10, v10, v92
	v_mul_f32 v11, v11, v93
	v_mul_f32 v6, v6, v110
	v_mul_f32 v7, v7, v111
	v_mul_f32 v2, v2, v202
	v_mul_f32 v3, v3, v203

.Lxjoin_fox:
	s_add_i32 s0, s9, 1
	s_cmp_lt_i32 s0, s25
	s_cselect_b64 s[22:23], -1, 0
	s_cmp_ge_i32 s0, s25
	s_cbranch_scc1 .LBB0_653
	v_add_u32_e32 v80, 0x41, v218
	v_mad_i64_i32 v[74:75], s[0:1], v80, s33, v[164:165]
	v_add_u32_e32 v81, 0x61, v218
	v_mad_i64_i32 v[78:79], s[0:1], v81, s33, v[164:165]
	global_load_dwordx4 v[146:149], v[74:75], off
	global_load_dwordx4 v[150:153], v[78:79], off
	v_mad_i64_i32 v[74:75], s[0:1], v80, s33, v[166:167]
	v_mad_i64_i32 v[78:79], s[0:1], v81, s33, v[166:167]
	global_load_dwordx4 v[154:157], v[74:75], off
	global_load_dwordx4 v[158:161], v[78:79], off

.Lp1join_dif_1:
	v_cmp_gt_f32_e32 vcc, 1.0, v181
	s_cmp_lt_u32 s29, 4
	s_cbranch_scc1 .Lxbar_dif
	s_cbranch_vccz .Lxb_dif
	s_and_saveexec_b64 s[0:1], s[38:39]
	ds_write_b32 v155, v181 offset:128
	s_or_b64 exec, exec, s[0:1]
	s_waitcnt lgkmcnt(0)
	ds_read_b128 v[134:137], v154 offset:224
	ds_read_b128 v[138:141], v154 offset:192
	ds_read_b128 v[142:145], v154 offset:160
	ds_read_b128 v[184:187], v154 offset:128
	s_waitcnt lgkmcnt(3)
	v_mul_f32 v64, v64, v136
	v_mul_f32 v65, v65, v137
	s_waitcnt lgkmcnt(2)
	v_mul_f32 v60, v60, v140
	v_mul_f32 v61, v61, v141
	s_waitcnt lgkmcnt(1)
	v_mul_f32 v56, v56, v144
	v_mul_f32 v57, v57, v145
	s_waitcnt lgkmcnt(0)
	v_mul_f32 v52, v52, v186
	v_mul_f32 v53, v53, v187
	v_mul_f32 v62, v62, v134
	v_mul_f32 v63, v63, v135
	v_mul_f32 v58, v58, v138
	v_mul_f32 v59, v59, v139
	v_mul_f32 v54, v54, v142
	v_mul_f32 v55, v55, v143
	v_mul_f32 v50, v50, v184
	v_mul_f32 v51, v51, v185
	v_mul_f32 v48, v48, v136
	v_mul_f32 v49, v49, v137
	v_mul_f32 v44, v44, v140
	v_mul_f32 v45, v45, v141
	v_mul_f32 v40, v40, v144
	v_mul_f32 v41, v41, v145
	v_mul_f32 v36, v36, v186
	v_mul_f32 v37, v37, v187
	v_mul_f32 v46, v46, v134
	v_mul_f32 v47, v47, v135
	v_mul_f32 v42, v42, v138
	v_mul_f32 v43, v43, v139
	v_mul_f32 v38, v38, v142
	v_mul_f32 v39, v39, v143
	v_mul_f32 v34, v34, v184
	v_mul_f32 v35, v35, v185
	v_mul_f32 v32, v32, v136
	v_mul_f32 v33, v33, v137
	v_mul_f32 v28, v28, v140
	v_mul_f32 v29, v29, v141
	v_mul_f32 v24, v24, v144
	v_mul_f32 v25, v25, v145
	v_mul_f32 v20, v20, v186
	v_mul_f32 v21, v21, v187
	v_mul_f32 v30, v30, v134
	v_mul_f32 v31, v31, v135
	v_mul_f32 v26, v26, v138
	v_mul_f32 v27, v27, v139
	v_mul_f32 v22, v22, v142
	v_mul_f32 v23, v23, v143
	v_mul_f32 v18, v18, v184
	v_mul_f32 v19, v19, v185
	v_mul_f32 v16, v16, v136
	v_mul_f32 v17, v17, v137
	v_mul_f32 v12, v12, v140
	v_mul_f32 v13, v13, v141
	v_mul_f32 v8, v8, v144
	v_mul_f32 v9, v9, v145
	v_mul_f32 v4, v4, v186
	v_mul_f32 v5, v5, v187
	v_mul_f32 v14, v14, v134
	v_mul_f32 v15, v15, v135
	v_mul_f32 v10, v10, v138
	v_mul_f32 v11, v11, v139
	v_mul_f32 v6, v6, v142
	v_mul_f32 v7, v7, v143
	v_mul_f32 v2, v2, v184
	v_mul_f32 v3, v3, v185
.Lxb_dif:
	v_cndmask_b32_e64 v132, v132, v168, s[40:41]
	v_mul_f32_e32 v183, 0xbe38aa3b, v132
	v_fmamk_f32 v82, v82, 0x3e38aa3b, v183
	v_fmamk_f32 v184, v66, 0x3e38aa3b, v183
	v_fmamk_f32 v66, v83, 0x3e38aa3b, v183
	v_fmamk_f32 v185, v67, 0x3e38aa3b, v183
	v_fmamk_f32 v67, v84, 0x3e38aa3b, v183
	v_fmamk_f32 v186, v68, 0x3e38aa3b, v183
	v_fmamk_f32 v68, v85, 0x3e38aa3b, v183
	v_fmamk_f32 v187, v69, 0x3e38aa3b, v183
	v_fmamk_f32 v69, v86, 0x3e38aa3b, v183
	v_fmamk_f32 v188, v70, 0x3e38aa3b, v183
	v_fmamk_f32 v70, v87, 0x3e38aa3b, v183
	v_fmamk_f32 v189, v71, 0x3e38aa3b, v183
	v_fmamk_f32 v71, v88, 0x3e38aa3b, v183
	v_fmamk_f32 v190, v72, 0x3e38aa3b, v183
	v_fmamk_f32 v72, v89, 0x3e38aa3b, v183
	v_fmamk_f32 v191, v73, 0x3e38aa3b, v183
	v_fmamk_f32 v73, v90, 0x3e38aa3b, v183
	v_fmamk_f32 v192, v74, 0x3e38aa3b, v183
	v_fmamk_f32 v74, v91, 0x3e38aa3b, v183
	v_fmamk_f32 v193, v75, 0x3e38aa3b, v183
	v_fmamk_f32 v75, v92, 0x3e38aa3b, v183
	v_fmamk_f32 v194, v76, 0x3e38aa3b, v183
	v_fmamk_f32 v76, v93, 0x3e38aa3b, v183
	v_fmamk_f32 v195, v77, 0x3e38aa3b, v183
	v_fmamk_f32 v77, v94, 0x3e38aa3b, v183
	v_fmamk_f32 v196, v78, 0x3e38aa3b, v183
	v_fmamk_f32 v78, v95, 0x3e38aa3b, v183
	v_fmamk_f32 v83, v96, 0x3e38aa3b, v183
	v_fmamk_f32 v84, v97, 0x3e38aa3b, v183
	v_exp_f32_e32 v146, v82
	v_exp_f32_e32 v168, v66
	v_exp_f32_e32 v144, v67
	v_exp_f32_e32 v147, v68
	v_exp_f32_e32 v142, v69
	v_exp_f32_e32 v145, v70
	v_exp_f32_e32 v141, v71
	v_exp_f32_e32 v143, v72
	v_exp_f32_e32 v138, v73
	v_exp_f32_e32 v140, v74
	v_exp_f32_e32 v136, v75
	v_exp_f32_e32 v139, v76
	v_exp_f32_e32 v134, v77
	v_exp_f32_e32 v137, v78
	v_exp_f32_e32 v133, v83
	v_exp_f32_e32 v135, v84
	v_fmamk_f32 v197, v79, 0x3e38aa3b, v183
	v_fmamk_f32 v198, v80, 0x3e38aa3b, v183
	v_fmac_f32_e32 v183, 0x3e38aa3b, v81
.Lxbar_dif:
	s_waitcnt vmcnt(2)
	ds_write_b128 v164, v[122:125] offset:32768
	s_waitcnt vmcnt(0)
	ds_write_b128 v164, v[126:129] offset:40960
	s_waitcnt lgkmcnt(0)
	s_barrier
	ds_write_b128 v165, v[114:117]
	ds_write_b128 v166, v[118:121]
	s_cmp_lt_u32 s29, 4
	s_cbranch_scc0 .Lxjoin_dif
	v_cmp_gt_f32_e32 vcc, 1.0, v181
	s_cbranch_vccz .LBB0_829
	s_and_saveexec_b64 s[0:1], s[38:39]
	ds_write_b32 v155, v181 offset:128
	s_or_b64 exec, exec, s[0:1]
	s_waitcnt lgkmcnt(0)
	ds_read_b128 v[134:137], v154 offset:224
	ds_read_b128 v[138:141], v154 offset:192
	ds_read_b128 v[142:145], v154 offset:160
	ds_read_b128 v[184:187], v154 offset:128
	s_waitcnt lgkmcnt(3)
	v_mul_f32 v64, v64, v136
	v_mul_f32 v65, v65, v137
	s_waitcnt lgkmcnt(2)
	v_mul_f32 v60, v60, v140
	v_mul_f32 v61, v61, v141
	s_waitcnt lgkmcnt(1)
	v_mul_f32 v56, v56, v144
	v_mul_f32 v57, v57, v145
	s_waitcnt lgkmcnt(0)
	v_mul_f32 v52, v52, v186
	v_mul_f32 v53, v53, v187
	v_mul_f32 v62, v62, v134
	v_mul_f32 v63, v63, v135
	v_mul_f32 v58, v58, v138
	v_mul_f32 v59, v59, v139
	v_mul_f32 v54, v54, v142
	v_mul_f32 v55, v55, v143
	v_mul_f32 v50, v50, v184
	v_mul_f32 v51, v51, v185
	v_mul_f32 v48, v48, v136
	v_mul_f32 v49, v49, v137
	v_mul_f32 v44, v44, v140
	v_mul_f32 v45, v45, v141
	v_mul_f32 v40, v40, v144
	v_mul_f32 v41, v41, v145
	v_mul_f32 v36, v36, v186
	v_mul_f32 v37, v37, v187
	v_mul_f32 v46, v46, v134
	v_mul_f32 v47, v47, v135
	v_mul_f32 v42, v42, v138
	v_mul_f32 v43, v43, v139
	v_mul_f32 v38, v38, v142
	v_mul_f32 v39, v39, v143
	v_mul_f32 v34, v34, v184
	v_mul_f32 v35, v35, v185
	v_mul_f32 v32, v32, v136
	v_mul_f32 v33, v33, v137
	v_mul_f32 v28, v28, v140
	v_mul_f32 v29, v29, v141
	v_mul_f32 v24, v24, v144
	v_mul_f32 v25, v25, v145
	v_mul_f32 v20, v20, v186
	v_mul_f32 v21, v21, v187
	v_mul_f32 v30, v30, v134
	v_mul_f32 v31, v31, v135
	v_mul_f32 v26, v26, v138
	v_mul_f32 v27, v27, v139
	v_mul_f32 v22, v22, v142
	v_mul_f32 v23, v23, v143
	v_mul_f32 v18, v18, v184
	v_mul_f32 v19, v19, v185
	v_mul_f32 v16, v16, v136
	v_mul_f32 v17, v17, v137
	v_mul_f32 v12, v12, v140
	v_mul_f32 v13, v13, v141
	v_mul_f32 v8, v8, v144
	v_mul_f32 v9, v9, v145
	v_mul_f32 v4, v4, v186
	v_mul_f32 v5, v5, v187
	v_mul_f32 v14, v14, v134
	v_mul_f32 v15, v15, v135
	v_mul_f32 v10, v10, v138
	v_mul_f32 v11, v11, v139
	v_mul_f32 v6, v6, v142
	v_mul_f32 v7, v7, v143
	v_mul_f32 v2, v2, v184
	v_mul_f32 v3, v3, v185

.Lxjoin_dif:
	s_add_i32 s0, s8, 1
	s_cmp_lt_i32 s0, s27
	s_cselect_b64 s[22:23], -1, 0
	s_cmp_ge_i32 s0, s27
	s_cbranch_scc1 .LBB0_831
	v_add_u32_e32 v66, 0x41, v182
	v_mad_i64_i32 v[66:67], s[0:1], v66, s33, v[130:131]
	v_add_u32_e32 v68, 0x61, v182
	v_mad_i64_i32 v[68:69], s[0:1], v68, s33, v[130:131]
	global_load_dwordx4 v[114:117], v[66:67], off offset:2048
	global_load_dwordx4 v[122:125], v[66:67], off offset:1024
	global_load_dwordx4 v[118:121], v[68:69], off offset:2048
	global_load_dwordx4 v[126:129], v[68:69], off offset:1024
